# prompt attention: C-operand bias init with 16 v_pk_add_f32 (neg, broadcast) instead of 32 v_sub_f32
# speedup vs baseline: 1.0009x; 1.0009x over previous
; #define LAS __attribute__((address_space(3)))
; __device__ __forceinline__ int crow(int r, int hi) { return (r & 3) + 8 * (r >> 2) + 4 * hi; }
; __device__ __forceinline__ void attn_tile(const LAS unsigned char* Kt, const LAS unsigned char* Vt, const LAS f32x4* ck, const bf16x8 (&qr)[4], const float cq2, const int kp0, const int qpos, const int qfirst, ...
;     ...
;             const bool first = (m_run == -INFINITY);
;             const float cbase = first ? cq2 : cqm;
; #pragma unroll
;             for (int g = 0; g < 4; ++g) { const f32x4 c0 = ck[2 * g + hi], c1 = ck[8 + 2 * g + hi];
; #pragma unroll
;                 for (int i = 0; i < 4; ++i) { p0[4 * g + i] = cbase - c0[i]; p1[4 * g + i] = cbase - c1[i]; } }
; #pragma unroll
;             for (int d0 = 0; d0 < 4; ++d0) {
;                 const bf16x8 k0 = *(const LAS bf16x8*)(Kt + r32 * 144 + d0 * 32 + hi * 16), k1 = *(const LAS bf16x8*)(Kt + (32 + r32) * 144 + d0 * 32 + hi * 16);
;                 p0 = __builtin_amdgcn_mfma_f32_32x32x16_bf16(k0, qr[d0], p0, 0, 0, 0); p1 = __builtin_amdgcn_mfma_f32_32x32x16_bf16(k1, qr[d0], p1, 0, 0, 0); }
;             if (kp0 + 63 > qfirst) {
; #pragma unroll
;                 for (int r = 0; r < 16; ++r) { const int kk = kp0 + crow(r, hi); if (kk > qpos) p0[r] = -INFINITY; if (kk + 32 > qpos) p1[r] = -INFINITY; } }
.LBB0_526:
	v_cmp_le_i32_e32 vcc, s13, v101
	s_and_b32 s18, s17, 1
	s_and_b64 s[0:1], s[70:71], vcc
	s_and_saveexec_b64 s[6:7], s[0:1]
	s_cbranch_execz .LBB0_536
	v_lshl_add_u32 v62, s18, 8, v98
	s_mul_i32 s10, s18, 0x2400
	v_add_u32_e32 v196, s10, v105
	ds_read_b128 v[50:53], v62 offset:39040
	ds_read_b128 v[34:37], v62 offset:38912
	ds_read_b128 v[38:41], v62 offset:38944
	ds_read_b128 v[54:57], v62 offset:39072
	ds_read_b128 v[42:45], v62 offset:38976
	ds_read_b128 v[58:61], v62 offset:39104
	ds_read_b128 v[46:49], v62 offset:39008
	ds_read_b128 v[62:65], v62 offset:39136
	ds_read_b128 v[110:113], v196 offset:4608
	ds_read_b128 v[114:117], v196
	ds_read_b128 v[118:121], v196 offset:32
	ds_read_b128 v[200:203], v196 offset:4640
	ds_read_b128 v[204:207], v196 offset:64
	ds_read_b128 v[208:211], v196 offset:4672
	ds_read_b128 v[212:215], v196 offset:96
	v_cmp_eq_f32_e64 s[0:1], s37, v108
	v_cmp_neq_f32_e32 vcc, s37, v108
	s_nop 0
	v_cndmask_b32_e64 v252, v1, v100, s[0:1]
	s_waitcnt lgkmcnt(8)
	v_pk_add_f32 v[48:49], v[252:253], v[48:49] op_sel_hi:[0,1] neg_lo:[0,1] neg_hi:[0,1]
	v_pk_add_f32 v[46:47], v[252:253], v[46:47] op_sel_hi:[0,1] neg_lo:[0,1] neg_hi:[0,1]
	v_pk_add_f32 v[44:45], v[252:253], v[44:45] op_sel_hi:[0,1] neg_lo:[0,1] neg_hi:[0,1]
	v_pk_add_f32 v[42:43], v[252:253], v[42:43] op_sel_hi:[0,1] neg_lo:[0,1] neg_hi:[0,1]
	v_pk_add_f32 v[40:41], v[252:253], v[40:41] op_sel_hi:[0,1] neg_lo:[0,1] neg_hi:[0,1]
	v_pk_add_f32 v[38:39], v[252:253], v[38:39] op_sel_hi:[0,1] neg_lo:[0,1] neg_hi:[0,1]
	v_pk_add_f32 v[36:37], v[252:253], v[36:37] op_sel_hi:[0,1] neg_lo:[0,1] neg_hi:[0,1]
	v_pk_add_f32 v[34:35], v[252:253], v[34:35] op_sel_hi:[0,1] neg_lo:[0,1] neg_hi:[0,1]
	ds_read_b128 v[216:219], v196 offset:4704
	s_waitcnt lgkmcnt(8)
	v_pk_add_f32 v[64:65], v[252:253], v[64:65] op_sel_hi:[0,1] neg_lo:[0,1] neg_hi:[0,1]
	v_pk_add_f32 v[62:63], v[252:253], v[62:63] op_sel_hi:[0,1] neg_lo:[0,1] neg_hi:[0,1]
	v_pk_add_f32 v[60:61], v[252:253], v[60:61] op_sel_hi:[0,1] neg_lo:[0,1] neg_hi:[0,1]
	v_pk_add_f32 v[58:59], v[252:253], v[58:59] op_sel_hi:[0,1] neg_lo:[0,1] neg_hi:[0,1]
	v_pk_add_f32 v[56:57], v[252:253], v[56:57] op_sel_hi:[0,1] neg_lo:[0,1] neg_hi:[0,1]
	v_pk_add_f32 v[54:55], v[252:253], v[54:55] op_sel_hi:[0,1] neg_lo:[0,1] neg_hi:[0,1]
	v_pk_add_f32 v[52:53], v[252:253], v[52:53] op_sel_hi:[0,1] neg_lo:[0,1] neg_hi:[0,1]
	v_pk_add_f32 v[50:51], v[252:253], v[50:51] op_sel_hi:[0,1] neg_lo:[0,1] neg_hi:[0,1]
	s_add_i32 s0, s13, 63
	v_cmp_gt_i32_e64 s[0:1], s0, v99
	s_waitcnt lgkmcnt(7)
	v_mfma_f32_32x32x16_bf16 v[50:65], v[110:113], v[66:69], v[50:65]
	s_waitcnt lgkmcnt(6)
	v_mfma_f32_32x32x16_bf16 v[34:49], v[114:117], v[66:69], v[34:49]
	s_waitcnt lgkmcnt(5)
	v_mfma_f32_32x32x16_bf16 v[34:49], v[118:121], v[70:73], v[34:49]
	s_waitcnt lgkmcnt(4)
	v_mfma_f32_32x32x16_bf16 v[50:65], v[200:203], v[70:73], v[50:65]
	s_waitcnt lgkmcnt(3)
	v_mfma_f32_32x32x16_bf16 v[34:49], v[204:207], v[74:77], v[34:49]
	s_waitcnt lgkmcnt(2)
	v_mfma_f32_32x32x16_bf16 v[50:65], v[208:211], v[74:77], v[50:65]
	s_waitcnt lgkmcnt(1)
	v_mfma_f32_32x32x16_bf16 v[34:49], v[212:215], v[78:81], v[34:49]
	s_waitcnt lgkmcnt(0)
	v_mfma_f32_32x32x16_bf16 v[50:65], v[216:219], v[78:81], v[50:65]
	s_and_saveexec_b64 s[10:11], s[0:1]
	s_cbranch_execz .LBB0_529
	v_add_u32_e32 v109, s13, v102
	v_add_u32_e32 v110, 32, v109
	v_cmp_le_i32_e64 s[0:1], v110, v92
	v_add_u32_e32 v110, 33, v109
	s_nop 5
	v_cndmask_b32_e64 v50, v137, v50, s[0:1]
	v_cmp_lt_i32_e64 s[0:1], v109, v92
	s_nop 1
	v_cndmask_b32_e64 v35, v137, v35, s[0:1]
	v_cmp_le_i32_e64 s[0:1], v109, v92
	s_nop 1
	v_cndmask_b32_e64 v34, v137, v34, s[0:1]
	v_cmp_le_i32_e64 s[0:1], v110, v92
	v_add_u32_e32 v110, 2, v109
	s_nop 0
	v_cndmask_b32_e64 v51, v137, v51, s[0:1]
	v_cmp_le_i32_e64 s[0:1], v110, v92
	v_add_u32_e32 v110, 34, v109
	s_nop 0
	v_cndmask_b32_e64 v36, v137, v36, s[0:1]
	v_cmp_le_i32_e64 s[0:1], v110, v92
	v_add_u32_e32 v110, 3, v109
	s_nop 0
	v_cndmask_b32_e64 v52, v137, v52, s[0:1]
	v_cmp_le_i32_e64 s[0:1], v110, v92
	v_add_u32_e32 v110, 35, v109
	s_nop 0
	v_cndmask_b32_e64 v37, v137, v37, s[0:1]
	v_cmp_le_i32_e64 s[0:1], v110, v92
	v_add_u32_e32 v110, 8, v109
	s_nop 0
	v_cndmask_b32_e64 v53, v137, v53, s[0:1]
	v_cmp_le_i32_e64 s[0:1], v110, v92
	v_add_u32_e32 v110, 40, v109
	s_nop 0
	v_cndmask_b32_e64 v38, v137, v38, s[0:1]
	v_cmp_le_i32_e64 s[0:1], v110, v92
	v_add_u32_e32 v110, 9, v109
	s_nop 0
	v_cndmask_b32_e64 v54, v137, v54, s[0:1]
	v_cmp_le_i32_e64 s[0:1], v110, v92
	v_add_u32_e32 v110, 41, v109
	s_nop 0
	v_cndmask_b32_e64 v39, v137, v39, s[0:1]
	v_cmp_le_i32_e64 s[0:1], v110, v92
	v_add_u32_e32 v110, 10, v109
	s_nop 0
	v_cndmask_b32_e64 v55, v137, v55, s[0:1]
	v_cmp_le_i32_e64 s[0:1], v110, v92
	v_add_u32_e32 v110, 42, v109
	s_nop 0
	v_cndmask_b32_e64 v40, v137, v40, s[0:1]
	v_cmp_le_i32_e64 s[0:1], v110, v92
	v_add_u32_e32 v110, 11, v109
	s_nop 0
	v_cndmask_b32_e64 v56, v137, v56, s[0:1]
	v_cmp_le_i32_e64 s[0:1], v110, v92
	v_add_u32_e32 v110, 43, v109
	s_nop 0
	v_cndmask_b32_e64 v41, v137, v41, s[0:1]
	v_cmp_le_i32_e64 s[0:1], v110, v92
	v_add_u32_e32 v110, 16, v109
	s_nop 0
	v_cndmask_b32_e64 v57, v137, v57, s[0:1]
	v_cmp_le_i32_e64 s[0:1], v110, v92
	v_add_u32_e32 v110, 48, v109
	s_nop 0
	v_cndmask_b32_e64 v42, v137, v42, s[0:1]
	v_cmp_le_i32_e64 s[0:1], v110, v92
	v_add_u32_e32 v110, 17, v109
	s_nop 0
	v_cndmask_b32_e64 v58, v137, v58, s[0:1]
	v_cmp_le_i32_e64 s[0:1], v110, v92
	v_add_u32_e32 v110, 49, v109
	s_nop 0
	v_cndmask_b32_e64 v43, v137, v43, s[0:1]
	v_cmp_le_i32_e64 s[0:1], v110, v92
	v_add_u32_e32 v110, 18, v109
	s_nop 0
	v_cndmask_b32_e64 v59, v137, v59, s[0:1]
	v_cmp_le_i32_e64 s[0:1], v110, v92
	v_add_u32_e32 v110, 50, v109
	s_nop 0
	v_cndmask_b32_e64 v44, v137, v44, s[0:1]
	v_cmp_le_i32_e64 s[0:1], v110, v92
	v_add_u32_e32 v110, 19, v109
	s_nop 0
	v_cndmask_b32_e64 v60, v137, v60, s[0:1]
	v_cmp_le_i32_e64 s[0:1], v110, v92
	v_add_u32_e32 v110, 51, v109
	s_nop 0
	v_cndmask_b32_e64 v45, v137, v45, s[0:1]
	v_cmp_le_i32_e64 s[0:1], v110, v92
	v_add_u32_e32 v110, 24, v109
	s_nop 0
	v_cndmask_b32_e64 v61, v137, v61, s[0:1]
	v_cmp_le_i32_e64 s[0:1], v110, v92
	v_add_u32_e32 v110, 56, v109
	s_nop 0
	v_cndmask_b32_e64 v46, v137, v46, s[0:1]
	v_cmp_le_i32_e64 s[0:1], v110, v92
	v_add_u32_e32 v110, 25, v109
	s_nop 0
	v_cndmask_b32_e64 v62, v137, v62, s[0:1]
	v_cmp_le_i32_e64 s[0:1], v110, v92
	v_add_u32_e32 v110, 57, v109
	s_nop 0
	v_cndmask_b32_e64 v47, v137, v47, s[0:1]
	v_cmp_le_i32_e64 s[0:1], v110, v92
	v_add_u32_e32 v110, 26, v109
	s_nop 0
	v_cndmask_b32_e64 v63, v137, v63, s[0:1]
	v_cmp_le_i32_e64 s[0:1], v110, v92
	v_add_u32_e32 v110, 58, v109
	s_nop 0
	v_cndmask_b32_e64 v48, v137, v48, s[0:1]
	v_cmp_le_i32_e64 s[0:1], v110, v92
	v_add_u32_e32 v110, 27, v109
	v_add_u32_e32 v109, 59, v109
	v_cndmask_b32_e64 v64, v137, v64, s[0:1]
	v_cmp_le_i32_e64 s[0:1], v110, v92
	s_nop 1
	v_cndmask_b32_e64 v49, v137, v49, s[0:1]
	v_cmp_le_i32_e64 s[0:1], v109, v92
	s_nop 1
	v_cndmask_b32_e64 v65, v137, v65, s[0:1]
